# ffn_out gemm_tile K-loop software-pipelined: fragment double-buffer in regs, DMA issue interleaved between MFMAs
# speedup vs baseline: 1.0022x; 1.0021x over previous
.LBB0_716:
	s_and_b32 s33, s56, 31
	s_ashr_i32 s46, s56, 5
	s_mul_i32 s40, s33, 0x160000
	s_add_u32 s44, s57, s40
	s_addc_u32 s45, s76, 0
	s_mul_i32 s41, s46, 0xb0000
	s_mul_hi_i32 s40, s46, 0xb0000
	s_add_u32 s50, s77, s41
	s_addc_u32 s51, s80, s40
	s_mul_i32 s40, s33, 5
	s_add_i32 s40, s40, s46
	v_mov_b32_e32 v102, v156
	s_mul_hi_i32 s41, s40, 0x2e8ba2e9
	s_lshr_b32 s47, s41, 31
	s_waitcnt vmcnt(0)
	v_ashrrev_i32_e32 v4, 6, v102
	v_bfe_u32 v0, v102, 3, 3
	s_ashr_i32 s41, s41, 3
	v_lshl_or_b32 v5, v4, 3, v0
	s_add_i32 s41, s41, s47
	v_lshrrev_b32_e32 v6, 1, v5
	s_mul_i32 s41, s41, 44
	v_xor_b32_e32 v6, v6, v102
	s_sub_i32 s40, s40, s41
	v_mov_b64_e32 v[0:1], s[44:45]
	s_movk_i32 s41, 0x1600
	v_lshlrev_b32_e32 v6, 4, v6
	v_mad_i64_i32 v[2:3], s[44:45], v5, s41, v[0:1]
	v_and_b32_e32 v144, 0x70, v6
	v_add_u32_e32 v6, 64, v5
	v_lshl_add_u64 v[64:65], v[2:3], 0, v[144:145]
	v_mad_i64_i32 v[2:3], s[44:45], v6, s41, v[0:1]
	v_lshl_add_u64 v[66:67], v[2:3], 0, v[144:145]
	v_add_u32_e32 v2, 0x80, v5
	v_mad_i64_i32 v[2:3], s[44:45], v2, s41, v[0:1]
	v_lshl_add_u64 v[68:69], v[2:3], 0, v[144:145]
	v_add_u32_e32 v2, 0xc0, v5
	v_mad_i64_i32 v[0:1], s[44:45], v2, s41, v[0:1]
	v_lshl_add_u64 v[70:71], v[0:1], 0, v[144:145]
	v_mov_b64_e32 v[0:1], s[50:51]
	v_and_b32_e32 v76, 63, v102
	v_mad_i64_i32 v[2:3], s[44:45], v5, s41, v[0:1]
	v_mad_i64_i32 v[0:1], s[44:45], v6, s41, v[0:1]
	v_lshl_add_u64 v[74:75], v[0:1], 0, v[144:145]
	v_lshlrev_b32_e32 v0, 4, v76
	v_lshl_or_b32 v0, v4, 10, v0
	s_lshl_b32 s44, s40, 6
	v_add_u32_e32 v84, 0, v0
	s_ashr_i32 s45, s44, 31
	v_lshl_add_u64 v[72:73], v[2:3], 0, v[144:145]
	s_lshl_b64 s[44:45], s[44:45], 1
	v_readfirstlane_b32 s41, v84
	v_add_u32_e32 v2, 0x2000, v84
	v_lshl_add_u64 v[0:1], v[64:65], 0, s[44:45]
	s_mov_b32 m0, s41
	v_readfirstlane_b32 s41, v2
	v_add_u32_e32 v2, 0x4000, v84
	s_waitcnt vmcnt(0)
	s_barrier
	global_load_lds_dwordx4 v[0:1], off
	v_lshl_add_u64 v[0:1], v[66:67], 0, s[44:45]
	s_mov_b32 m0, s41
	v_readfirstlane_b32 s41, v2
	v_add_u32_e32 v2, 0x6000, v84
	global_load_lds_dwordx4 v[0:1], off
	v_lshl_add_u64 v[0:1], v[68:69], 0, s[44:45]
	s_mov_b32 m0, s41
	v_readfirstlane_b32 s41, v2
	v_add_u32_e32 v2, 0x8000, v84
	global_load_lds_dwordx4 v[0:1], off
	v_lshl_add_u64 v[0:1], v[70:71], 0, s[44:45]
	s_mov_b32 m0, s41
	v_readfirstlane_b32 s41, v2
	v_add_u32_e32 v2, 0xa000, v84
	global_load_lds_dwordx4 v[0:1], off
	v_lshl_add_u64 v[0:1], v[72:73], 0, s[44:45]
	s_mov_b32 m0, s41
	v_readfirstlane_b32 s41, v2
	s_cmp_lt_i32 s40, 43
	global_load_lds_dwordx4 v[0:1], off
	s_mov_b32 m0, s41
	s_cselect_b32 s41, 0, 0xffffffd4
	s_add_i32 s41, s40, s41
	s_lshl_b32 s41, s41, 6
	v_lshl_add_u64 v[0:1], v[74:75], 0, s[44:45]
	s_add_i32 s44, s41, 64
	v_add_u32_e32 v2, 0xc000, v84
	s_ashr_i32 s45, s44, 31
	s_lshl_b64 s[44:45], s[44:45], 1
	v_readfirstlane_b32 s41, v2
	v_add_u32_e32 v2, 0xe000, v84
	global_load_lds_dwordx4 v[0:1], off
	v_lshl_add_u64 v[0:1], v[64:65], 0, s[44:45]
	s_mov_b32 m0, s41
	v_readfirstlane_b32 s41, v2
	v_add_u32_e32 v2, 0x10000, v84
	global_load_lds_dwordx4 v[0:1], off
	v_lshl_add_u64 v[0:1], v[66:67], 0, s[44:45]
	s_mov_b32 m0, s41
	v_readfirstlane_b32 s41, v2
	v_add_u32_e32 v2, 0x12000, v84
	global_load_lds_dwordx4 v[0:1], off
	v_lshl_add_u64 v[0:1], v[68:69], 0, s[44:45]
	s_mov_b32 m0, s41
	v_readfirstlane_b32 s41, v2
	v_add_u32_e32 v2, 0x14000, v84
	global_load_lds_dwordx4 v[0:1], off
	v_lshl_add_u64 v[0:1], v[70:71], 0, s[44:45]
	s_mov_b32 m0, s41
	v_readfirstlane_b32 s41, v2
	v_add_u32_e32 v2, 0x16000, v84
	global_load_lds_dwordx4 v[0:1], off
	v_lshl_add_u64 v[0:1], v[72:73], 0, s[44:45]
	s_mov_b32 m0, s41
	v_readfirstlane_b32 s41, v2
	global_load_lds_dwordx4 v[0:1], off
	v_lshl_add_u64 v[0:1], v[74:75], 0, s[44:45]
	s_mov_b32 m0, s41
	v_and_b32_e32 v114, 15, v102
	global_load_lds_dwordx4 v[0:1], off
	v_and_b32_e32 v77, 1, v4
	v_bfe_u32 v79, v102, 4, 2
	v_bfe_u32 v0, v102, 1, 3
	v_ashrrev_i32_e32 v78, 7, v102
	v_lshlrev_b32_e32 v1, 7, v114
	v_xor_b32_e32 v2, v79, v0
	v_bitop3_b32 v0, v79, v0, 4 bitop3:0x36
	v_lshlrev_b32_e32 v3, 13, v77
	v_lshlrev_b32_e32 v0, 4, v0
	v_or3_b32 v3, v3, v1, s95
	v_lshl_or_b32 v1, v78, 13, v1
	v_lshlrev_b32_e32 v2, 4, v2
	v_or_b32_e32 v80, v0, v1
	v_or_b32_e32 v83, v3, v0
	v_mov_b32_e32 v0, 0
	v_or_b32_e32 v81, v3, v2
	v_or_b32_e32 v82, v2, v1
	s_mov_b32 s41, 0
	s_mov_b32 s44, 2
	v_mov_b32_e32 v1, v0
	v_mov_b32_e32 v2, v0
	v_mov_b32_e32 v3, v0
	v_mov_b32_e32 v4, v0
	v_mov_b32_e32 v5, v0
	v_mov_b32_e32 v6, v0
	v_mov_b32_e32 v7, v0
	v_mov_b32_e32 v8, v0
	v_mov_b32_e32 v9, v0
	v_mov_b32_e32 v10, v0
	v_mov_b32_e32 v11, v0
	v_mov_b32_e32 v12, v0
	v_mov_b32_e32 v13, v0
	v_mov_b32_e32 v14, v0
	v_mov_b32_e32 v15, v0
	v_mov_b32_e32 v16, v0
	v_mov_b32_e32 v17, v0
	v_mov_b32_e32 v18, v0
	v_mov_b32_e32 v19, v0
	v_mov_b32_e32 v20, v0
	v_mov_b32_e32 v21, v0
	v_mov_b32_e32 v22, v0
	v_mov_b32_e32 v23, v0
	v_mov_b32_e32 v24, v0
	v_mov_b32_e32 v25, v0
	v_mov_b32_e32 v26, v0
	v_mov_b32_e32 v27, v0
	v_mov_b32_e32 v28, v0
	v_mov_b32_e32 v29, v0
	v_mov_b32_e32 v30, v0
	v_mov_b32_e32 v31, v0
	v_mov_b32_e32 v36, v0
	v_mov_b32_e32 v37, v0
	v_mov_b32_e32 v38, v0
	v_mov_b32_e32 v39, v0
	v_mov_b32_e32 v44, v0
	v_mov_b32_e32 v45, v0
	v_mov_b32_e32 v46, v0
	v_mov_b32_e32 v47, v0
	v_mov_b32_e32 v32, v0
	v_mov_b32_e32 v33, v0
	v_mov_b32_e32 v34, v0
	v_mov_b32_e32 v35, v0
	v_mov_b32_e32 v40, v0
	v_mov_b32_e32 v41, v0
	v_mov_b32_e32 v42, v0
	v_mov_b32_e32 v43, v0
	v_mov_b32_e32 v48, v0
	v_mov_b32_e32 v49, v0
	v_mov_b32_e32 v50, v0
	v_mov_b32_e32 v51, v0
	v_mov_b32_e32 v52, v0
	v_mov_b32_e32 v53, v0
	v_mov_b32_e32 v54, v0
	v_mov_b32_e32 v55, v0
	v_mov_b32_e32 v56, v0
	v_mov_b32_e32 v57, v0
	v_mov_b32_e32 v58, v0
	v_mov_b32_e32 v59, v0
	v_mov_b32_e32 v60, v0
	v_mov_b32_e32 v61, v0
	v_mov_b32_e32 v62, v0
	v_mov_b32_e32 v63, v0
	s_waitcnt vmcnt(6)
	s_mul_i32 s45, s41, 0xc000
	s_add_i32 s47, s45, 0
	s_barrier
	v_add_u32_e32 v85, s47, v81
	v_add_u32_e32 v103, s47, v82
	ds_read_b128 v[86:89], v85 offset:0
	ds_read_b128 v[90:93], v85 offset:0x800
	ds_read_b128 v[94:97], v85 offset:0x1000
	ds_read_b128 v[98:101], v85 offset:0x1800
	ds_read_b128 v[104:107], v103 offset:0
	ds_read_b128 v[108:111], v103 offset:0x800
	ds_read_b128 v[116:119], v103 offset:0x1000
	ds_read_b128 v[120:123], v103 offset:0x1800
	v_add_u32_e32 v112, s47, v83
	v_add_u32_e32 v113, s47, v80
	ds_read_b128 v[124:127], v112 offset:0
	ds_read_b128 v[128:131], v112 offset:0x800
	ds_read_b128 v[132:135], v112 offset:0x1000
	ds_read_b128 v[136:139], v112 offset:0x1800
	ds_read_b128 v[140:143], v113 offset:0
	ds_read_b128 v[148:151], v113 offset:0x800
	ds_read_b128 v[152:155], v113 offset:0x1000
	ds_read_b128 v[174:177], v113 offset:0x1800
	s_add_i32 s45, s45, 0xffff4000
	s_cmp_gt_i32 s41, 0
	s_cselect_b32 s45, s45, 0x18000
	v_add_u32_e32 v85, s45, v84
	s_add_i32 s45, s40, s44
	s_cmp_lt_i32 s45, 44
	s_cselect_b32 s47, 0, 0xffffffd4
	s_add_i32 s45, s45, s47
	s_lshl_b32 s50, s45, 6
	s_ashr_i32 s51, s50, 31
	s_lshl_b64 s[50:51], s[50:51], 1
	v_readfirstlane_b32 s45, v85
	v_add_u32_e32 v244, 0x2000, v85
	v_lshl_add_u64 v[242:243], v[64:65], 0, s[50:51]
	s_mov_b32 m0, s45
	v_readfirstlane_b32 s45, v244
	v_add_u32_e32 v244, 0x4000, v85
	global_load_lds_dwordx4 v[242:243], off
	v_lshl_add_u64 v[242:243], v[66:67], 0, s[50:51]
	s_mov_b32 m0, s45
	v_readfirstlane_b32 s45, v244
	v_add_u32_e32 v244, 0x6000, v85
	global_load_lds_dwordx4 v[242:243], off
	v_lshl_add_u64 v[242:243], v[68:69], 0, s[50:51]
	s_mov_b32 m0, s45
	v_readfirstlane_b32 s45, v244
	v_add_u32_e32 v244, 0x8000, v85
	global_load_lds_dwordx4 v[242:243], off
	v_lshl_add_u64 v[242:243], v[70:71], 0, s[50:51]
	s_mov_b32 m0, s45
	v_readfirstlane_b32 s45, v244
	v_add_u32_e32 v85, 0xa000, v85
	global_load_lds_dwordx4 v[242:243], off
	v_lshl_add_u64 v[242:243], v[72:73], 0, s[50:51]
	s_mov_b32 m0, s45
	v_readfirstlane_b32 s45, v85
	global_load_lds_dwordx4 v[242:243], off
	v_lshl_add_u64 v[242:243], v[74:75], 0, s[50:51]
	s_mov_b32 m0, s45
	s_nop 0
	global_load_lds_dwordx4 v[242:243], off
	s_waitcnt lgkmcnt(0)
	s_add_i32 s45, s41, 1
	s_cmp_lg_u32 s41, 2
	s_cselect_b32 s41, s45, 0
	s_add_i32 s44, s44, 1
.Lpp2_loop:
	s_waitcnt vmcnt(6)
	s_mul_i32 s45, s41, 0xc000
	s_add_i32 s47, s45, 0
	s_barrier
	v_add_u32_e32 v85, s47, v81
	v_add_u32_e32 v103, s47, v82
	ds_read_b128 v[178:181], v85 offset:0
	ds_read_b128 v[182:185], v85 offset:0x800
	ds_read_b128 v[186:189], v85 offset:0x1000
	ds_read_b128 v[190:193], v85 offset:0x1800
	ds_read_b128 v[194:197], v103 offset:0
	ds_read_b128 v[198:201], v103 offset:0x800
	ds_read_b128 v[202:205], v103 offset:0x1000
	ds_read_b128 v[206:209], v103 offset:0x1800
	v_add_u32_e32 v112, s47, v83
	v_add_u32_e32 v113, s47, v80
	ds_read_b128 v[210:213], v112 offset:0
	ds_read_b128 v[214:217], v112 offset:0x800
	ds_read_b128 v[218:221], v112 offset:0x1000
	ds_read_b128 v[222:225], v112 offset:0x1800
	ds_read_b128 v[226:229], v113 offset:0
	ds_read_b128 v[230:233], v113 offset:0x800
	ds_read_b128 v[234:237], v113 offset:0x1000
	ds_read_b128 v[238:241], v113 offset:0x1800
	v_mfma_f32_16x16x32_bf16 v[44:47], v[86:89], v[104:107], v[44:47]
	s_add_i32 s45, s45, 0xffff4000
	s_cmp_gt_i32 s41, 0
	s_cselect_b32 s45, s45, 0x18000
	v_add_u32_e32 v85, s45, v84
	v_mfma_f32_16x16x32_bf16 v[36:39], v[90:93], v[104:107], v[36:39]
	s_add_i32 s45, s40, s44
	s_cmp_lt_i32 s45, 44
	s_cselect_b32 s47, 0, 0xffffffd4
	s_add_i32 s45, s45, s47
	v_mfma_f32_16x16x32_bf16 v[28:31], v[94:97], v[104:107], v[28:31]
	s_lshl_b32 s50, s45, 6
	s_ashr_i32 s51, s50, 31
	s_lshl_b64 s[50:51], s[50:51], 1
	v_readfirstlane_b32 s45, v85
	v_mfma_f32_16x16x32_bf16 v[24:27], v[98:101], v[104:107], v[24:27]
	v_add_u32_e32 v244, 0x2000, v85
	v_lshl_add_u64 v[242:243], v[64:65], 0, s[50:51]
	s_mov_b32 m0, s45
	v_mfma_f32_16x16x32_bf16 v[20:23], v[86:89], v[108:111], v[20:23]
	v_readfirstlane_b32 s45, v244
	v_add_u32_e32 v244, 0x4000, v85
	global_load_lds_dwordx4 v[242:243], off
	v_mfma_f32_16x16x32_bf16 v[16:19], v[90:93], v[108:111], v[16:19]
	v_lshl_add_u64 v[242:243], v[66:67], 0, s[50:51]
	v_mfma_f32_16x16x32_bf16 v[12:15], v[94:97], v[108:111], v[12:15]
	s_mov_b32 m0, s45
	v_mfma_f32_16x16x32_bf16 v[8:11], v[98:101], v[108:111], v[8:11]
	v_readfirstlane_b32 s45, v244
	v_mfma_f32_16x16x32_bf16 v[4:7], v[86:89], v[116:119], v[4:7]
	v_add_u32_e32 v244, 0x6000, v85
	v_mfma_f32_16x16x32_bf16 v[0:3], v[90:93], v[116:119], v[0:3]
	global_load_lds_dwordx4 v[242:243], off
	v_mfma_f32_16x16x32_bf16 v[32:35], v[94:97], v[116:119], v[32:35]
	v_lshl_add_u64 v[242:243], v[68:69], 0, s[50:51]
	v_mfma_f32_16x16x32_bf16 v[40:43], v[98:101], v[116:119], v[40:43]
	s_mov_b32 m0, s45
	v_mfma_f32_16x16x32_bf16 v[48:51], v[86:89], v[120:123], v[48:51]
	v_readfirstlane_b32 s45, v244
	v_mfma_f32_16x16x32_bf16 v[52:55], v[90:93], v[120:123], v[52:55]
	v_add_u32_e32 v244, 0x8000, v85
	v_mfma_f32_16x16x32_bf16 v[56:59], v[94:97], v[120:123], v[56:59]
	global_load_lds_dwordx4 v[242:243], off
	v_mfma_f32_16x16x32_bf16 v[60:63], v[98:101], v[120:123], v[60:63]
	v_lshl_add_u64 v[242:243], v[70:71], 0, s[50:51]
	v_mfma_f32_16x16x32_bf16 v[44:47], v[124:127], v[140:143], v[44:47]
	s_mov_b32 m0, s45
	v_mfma_f32_16x16x32_bf16 v[36:39], v[128:131], v[140:143], v[36:39]
	v_readfirstlane_b32 s45, v244
	v_mfma_f32_16x16x32_bf16 v[28:31], v[132:135], v[140:143], v[28:31]
	v_add_u32_e32 v85, 0xa000, v85
	v_mfma_f32_16x16x32_bf16 v[24:27], v[136:139], v[140:143], v[24:27]
	global_load_lds_dwordx4 v[242:243], off
	v_mfma_f32_16x16x32_bf16 v[20:23], v[124:127], v[148:151], v[20:23]
	v_lshl_add_u64 v[242:243], v[72:73], 0, s[50:51]
	v_mfma_f32_16x16x32_bf16 v[16:19], v[128:131], v[148:151], v[16:19]
	s_mov_b32 m0, s45
	v_mfma_f32_16x16x32_bf16 v[12:15], v[132:135], v[148:151], v[12:15]
	v_readfirstlane_b32 s45, v85
	v_mfma_f32_16x16x32_bf16 v[8:11], v[136:139], v[148:151], v[8:11]
	global_load_lds_dwordx4 v[242:243], off
	v_mfma_f32_16x16x32_bf16 v[4:7], v[124:127], v[152:155], v[4:7]
	v_mfma_f32_16x16x32_bf16 v[0:3], v[128:131], v[152:155], v[0:3]
	v_lshl_add_u64 v[242:243], v[74:75], 0, s[50:51]
	v_mfma_f32_16x16x32_bf16 v[32:35], v[132:135], v[152:155], v[32:35]
	s_mov_b32 m0, s45
	v_mfma_f32_16x16x32_bf16 v[40:43], v[136:139], v[152:155], v[40:43]
	s_nop 0
	v_mfma_f32_16x16x32_bf16 v[48:51], v[124:127], v[174:177], v[48:51]
	global_load_lds_dwordx4 v[242:243], off
	v_mfma_f32_16x16x32_bf16 v[52:55], v[128:131], v[174:177], v[52:55]
	v_mfma_f32_16x16x32_bf16 v[56:59], v[132:135], v[174:177], v[56:59]
	v_mfma_f32_16x16x32_bf16 v[60:63], v[136:139], v[174:177], v[60:63]
	s_waitcnt lgkmcnt(0)
	s_add_i32 s45, s41, 1
	s_cmp_lg_u32 s41, 2
	s_cselect_b32 s41, s45, 0
	s_add_i32 s44, s44, 1
	s_waitcnt vmcnt(6)
	s_mul_i32 s45, s41, 0xc000
	s_add_i32 s47, s45, 0
	s_barrier
	v_add_u32_e32 v85, s47, v81
	v_add_u32_e32 v103, s47, v82
	ds_read_b128 v[86:89], v85 offset:0
	ds_read_b128 v[90:93], v85 offset:0x800
	ds_read_b128 v[94:97], v85 offset:0x1000
	ds_read_b128 v[98:101], v85 offset:0x1800
	ds_read_b128 v[104:107], v103 offset:0
	ds_read_b128 v[108:111], v103 offset:0x800
	ds_read_b128 v[116:119], v103 offset:0x1000
	ds_read_b128 v[120:123], v103 offset:0x1800
	v_add_u32_e32 v112, s47, v83
	v_add_u32_e32 v113, s47, v80
	ds_read_b128 v[124:127], v112 offset:0
	ds_read_b128 v[128:131], v112 offset:0x800
	ds_read_b128 v[132:135], v112 offset:0x1000
	ds_read_b128 v[136:139], v112 offset:0x1800
	ds_read_b128 v[140:143], v113 offset:0
	ds_read_b128 v[148:151], v113 offset:0x800
	ds_read_b128 v[152:155], v113 offset:0x1000
	ds_read_b128 v[174:177], v113 offset:0x1800
	v_mfma_f32_16x16x32_bf16 v[44:47], v[178:181], v[194:197], v[44:47]
	s_add_i32 s45, s45, 0xffff4000
	s_cmp_gt_i32 s41, 0
	s_cselect_b32 s45, s45, 0x18000
	v_add_u32_e32 v85, s45, v84
	v_mfma_f32_16x16x32_bf16 v[36:39], v[182:185], v[194:197], v[36:39]
	s_add_i32 s45, s40, s44
	s_cmp_lt_i32 s45, 44
	s_cselect_b32 s47, 0, 0xffffffd4
	s_add_i32 s45, s45, s47
	v_mfma_f32_16x16x32_bf16 v[28:31], v[186:189], v[194:197], v[28:31]
	s_lshl_b32 s50, s45, 6
	s_ashr_i32 s51, s50, 31
	s_lshl_b64 s[50:51], s[50:51], 1
	v_readfirstlane_b32 s45, v85
	v_mfma_f32_16x16x32_bf16 v[24:27], v[190:193], v[194:197], v[24:27]
	v_add_u32_e32 v244, 0x2000, v85
	v_lshl_add_u64 v[242:243], v[64:65], 0, s[50:51]
	s_mov_b32 m0, s45
	v_mfma_f32_16x16x32_bf16 v[20:23], v[178:181], v[198:201], v[20:23]
	v_readfirstlane_b32 s45, v244
	v_add_u32_e32 v244, 0x4000, v85
	global_load_lds_dwordx4 v[242:243], off
	v_mfma_f32_16x16x32_bf16 v[16:19], v[182:185], v[198:201], v[16:19]
	v_lshl_add_u64 v[242:243], v[66:67], 0, s[50:51]
	v_mfma_f32_16x16x32_bf16 v[12:15], v[186:189], v[198:201], v[12:15]
	s_mov_b32 m0, s45
	v_mfma_f32_16x16x32_bf16 v[8:11], v[190:193], v[198:201], v[8:11]
	v_readfirstlane_b32 s45, v244
	v_mfma_f32_16x16x32_bf16 v[4:7], v[178:181], v[202:205], v[4:7]
	v_add_u32_e32 v244, 0x6000, v85
	v_mfma_f32_16x16x32_bf16 v[0:3], v[182:185], v[202:205], v[0:3]
	global_load_lds_dwordx4 v[242:243], off
	v_mfma_f32_16x16x32_bf16 v[32:35], v[186:189], v[202:205], v[32:35]
	v_lshl_add_u64 v[242:243], v[68:69], 0, s[50:51]
	v_mfma_f32_16x16x32_bf16 v[40:43], v[190:193], v[202:205], v[40:43]
	s_mov_b32 m0, s45
	v_mfma_f32_16x16x32_bf16 v[48:51], v[178:181], v[206:209], v[48:51]
	v_readfirstlane_b32 s45, v244
	v_mfma_f32_16x16x32_bf16 v[52:55], v[182:185], v[206:209], v[52:55]
	v_add_u32_e32 v244, 0x8000, v85
	v_mfma_f32_16x16x32_bf16 v[56:59], v[186:189], v[206:209], v[56:59]
	global_load_lds_dwordx4 v[242:243], off
	v_mfma_f32_16x16x32_bf16 v[60:63], v[190:193], v[206:209], v[60:63]
	v_lshl_add_u64 v[242:243], v[70:71], 0, s[50:51]
	v_mfma_f32_16x16x32_bf16 v[44:47], v[210:213], v[226:229], v[44:47]
	s_mov_b32 m0, s45
	v_mfma_f32_16x16x32_bf16 v[36:39], v[214:217], v[226:229], v[36:39]
	v_readfirstlane_b32 s45, v244
	v_mfma_f32_16x16x32_bf16 v[28:31], v[218:221], v[226:229], v[28:31]
	v_add_u32_e32 v85, 0xa000, v85
	v_mfma_f32_16x16x32_bf16 v[24:27], v[222:225], v[226:229], v[24:27]
	global_load_lds_dwordx4 v[242:243], off
	v_mfma_f32_16x16x32_bf16 v[20:23], v[210:213], v[230:233], v[20:23]
	v_lshl_add_u64 v[242:243], v[72:73], 0, s[50:51]
	v_mfma_f32_16x16x32_bf16 v[16:19], v[214:217], v[230:233], v[16:19]
	s_mov_b32 m0, s45
	v_mfma_f32_16x16x32_bf16 v[12:15], v[218:221], v[230:233], v[12:15]
	v_readfirstlane_b32 s45, v85
	v_mfma_f32_16x16x32_bf16 v[8:11], v[222:225], v[230:233], v[8:11]
	global_load_lds_dwordx4 v[242:243], off
	v_mfma_f32_16x16x32_bf16 v[4:7], v[210:213], v[234:237], v[4:7]
	v_mfma_f32_16x16x32_bf16 v[0:3], v[214:217], v[234:237], v[0:3]
	v_lshl_add_u64 v[242:243], v[74:75], 0, s[50:51]
	v_mfma_f32_16x16x32_bf16 v[32:35], v[218:221], v[234:237], v[32:35]
	s_mov_b32 m0, s45
	v_mfma_f32_16x16x32_bf16 v[40:43], v[222:225], v[234:237], v[40:43]
	s_nop 0
	v_mfma_f32_16x16x32_bf16 v[48:51], v[210:213], v[238:241], v[48:51]
	global_load_lds_dwordx4 v[242:243], off
	v_mfma_f32_16x16x32_bf16 v[52:55], v[214:217], v[238:241], v[52:55]
	v_mfma_f32_16x16x32_bf16 v[56:59], v[218:221], v[238:241], v[56:59]
	v_mfma_f32_16x16x32_bf16 v[60:63], v[222:225], v[238:241], v[60:63]
	s_waitcnt lgkmcnt(0)
	s_add_i32 s45, s41, 1
	s_cmp_lg_u32 s41, 2
	s_cselect_b32 s41, s45, 0
	s_add_i32 s44, s44, 1
	s_cmp_eq_u32 s44, 43
	s_cbranch_scc0 .Lpp2_loop
	s_waitcnt vmcnt(6)
	s_mul_i32 s45, s41, 0xc000
	s_add_i32 s47, s45, 0
	s_barrier
	v_add_u32_e32 v85, s47, v81
	v_add_u32_e32 v103, s47, v82
	ds_read_b128 v[178:181], v85 offset:0
	ds_read_b128 v[182:185], v85 offset:0x800
	ds_read_b128 v[186:189], v85 offset:0x1000
	ds_read_b128 v[190:193], v85 offset:0x1800
	ds_read_b128 v[194:197], v103 offset:0
	ds_read_b128 v[198:201], v103 offset:0x800
	ds_read_b128 v[202:205], v103 offset:0x1000
	ds_read_b128 v[206:209], v103 offset:0x1800
	v_add_u32_e32 v112, s47, v83
	v_add_u32_e32 v113, s47, v80
	ds_read_b128 v[210:213], v112 offset:0
	ds_read_b128 v[214:217], v112 offset:0x800
	ds_read_b128 v[218:221], v112 offset:0x1000
	ds_read_b128 v[222:225], v112 offset:0x1800
	ds_read_b128 v[226:229], v113 offset:0
	ds_read_b128 v[230:233], v113 offset:0x800
	ds_read_b128 v[234:237], v113 offset:0x1000
	ds_read_b128 v[238:241], v113 offset:0x1800
	v_mfma_f32_16x16x32_bf16 v[44:47], v[86:89], v[104:107], v[44:47]
	s_add_i32 s45, s45, 0xffff4000
	s_cmp_gt_i32 s41, 0
	s_cselect_b32 s45, s45, 0x18000
	v_add_u32_e32 v85, s45, v84
	v_mfma_f32_16x16x32_bf16 v[36:39], v[90:93], v[104:107], v[36:39]
	s_add_i32 s45, s40, s44
	s_cmp_lt_i32 s45, 44
	s_cselect_b32 s47, 0, 0xffffffd4
	s_add_i32 s45, s45, s47
	v_mfma_f32_16x16x32_bf16 v[28:31], v[94:97], v[104:107], v[28:31]
	s_lshl_b32 s50, s45, 6
	s_ashr_i32 s51, s50, 31
	s_lshl_b64 s[50:51], s[50:51], 1
	v_readfirstlane_b32 s45, v85
	v_mfma_f32_16x16x32_bf16 v[24:27], v[98:101], v[104:107], v[24:27]
	v_add_u32_e32 v244, 0x2000, v85
	v_lshl_add_u64 v[242:243], v[64:65], 0, s[50:51]
	s_mov_b32 m0, s45
	v_mfma_f32_16x16x32_bf16 v[20:23], v[86:89], v[108:111], v[20:23]
	v_readfirstlane_b32 s45, v244
	v_add_u32_e32 v244, 0x4000, v85
	global_load_lds_dwordx4 v[242:243], off
	v_mfma_f32_16x16x32_bf16 v[16:19], v[90:93], v[108:111], v[16:19]
	v_lshl_add_u64 v[242:243], v[66:67], 0, s[50:51]
	v_mfma_f32_16x16x32_bf16 v[12:15], v[94:97], v[108:111], v[12:15]
	s_mov_b32 m0, s45
	v_mfma_f32_16x16x32_bf16 v[8:11], v[98:101], v[108:111], v[8:11]
	v_readfirstlane_b32 s45, v244
	v_mfma_f32_16x16x32_bf16 v[4:7], v[86:89], v[116:119], v[4:7]
	v_add_u32_e32 v244, 0x6000, v85
	v_mfma_f32_16x16x32_bf16 v[0:3], v[90:93], v[116:119], v[0:3]
	global_load_lds_dwordx4 v[242:243], off
	v_mfma_f32_16x16x32_bf16 v[32:35], v[94:97], v[116:119], v[32:35]
	v_lshl_add_u64 v[242:243], v[68:69], 0, s[50:51]
	v_mfma_f32_16x16x32_bf16 v[40:43], v[98:101], v[116:119], v[40:43]
	s_mov_b32 m0, s45
	v_mfma_f32_16x16x32_bf16 v[48:51], v[86:89], v[120:123], v[48:51]
	v_readfirstlane_b32 s45, v244
	v_mfma_f32_16x16x32_bf16 v[52:55], v[90:93], v[120:123], v[52:55]
	v_add_u32_e32 v244, 0x8000, v85
	v_mfma_f32_16x16x32_bf16 v[56:59], v[94:97], v[120:123], v[56:59]
	global_load_lds_dwordx4 v[242:243], off
	v_mfma_f32_16x16x32_bf16 v[60:63], v[98:101], v[120:123], v[60:63]
	v_lshl_add_u64 v[242:243], v[70:71], 0, s[50:51]
	v_mfma_f32_16x16x32_bf16 v[44:47], v[124:127], v[140:143], v[44:47]
	s_mov_b32 m0, s45
	v_mfma_f32_16x16x32_bf16 v[36:39], v[128:131], v[140:143], v[36:39]
	v_readfirstlane_b32 s45, v244
	v_mfma_f32_16x16x32_bf16 v[28:31], v[132:135], v[140:143], v[28:31]
	v_add_u32_e32 v85, 0xa000, v85
	v_mfma_f32_16x16x32_bf16 v[24:27], v[136:139], v[140:143], v[24:27]
	global_load_lds_dwordx4 v[242:243], off
	v_mfma_f32_16x16x32_bf16 v[20:23], v[124:127], v[148:151], v[20:23]
	v_lshl_add_u64 v[242:243], v[72:73], 0, s[50:51]
	v_mfma_f32_16x16x32_bf16 v[16:19], v[128:131], v[148:151], v[16:19]
	s_mov_b32 m0, s45
	v_mfma_f32_16x16x32_bf16 v[12:15], v[132:135], v[148:151], v[12:15]
	v_readfirstlane_b32 s45, v85
	v_mfma_f32_16x16x32_bf16 v[8:11], v[136:139], v[148:151], v[8:11]
	global_load_lds_dwordx4 v[242:243], off
	v_mfma_f32_16x16x32_bf16 v[4:7], v[124:127], v[152:155], v[4:7]
	v_mfma_f32_16x16x32_bf16 v[0:3], v[128:131], v[152:155], v[0:3]
	v_lshl_add_u64 v[242:243], v[74:75], 0, s[50:51]
	v_mfma_f32_16x16x32_bf16 v[32:35], v[132:135], v[152:155], v[32:35]
	s_mov_b32 m0, s45
	v_mfma_f32_16x16x32_bf16 v[40:43], v[136:139], v[152:155], v[40:43]
	s_nop 0
	v_mfma_f32_16x16x32_bf16 v[48:51], v[124:127], v[174:177], v[48:51]
	global_load_lds_dwordx4 v[242:243], off
	v_mfma_f32_16x16x32_bf16 v[52:55], v[128:131], v[174:177], v[52:55]
	v_mfma_f32_16x16x32_bf16 v[56:59], v[132:135], v[174:177], v[56:59]
	v_mfma_f32_16x16x32_bf16 v[60:63], v[136:139], v[174:177], v[60:63]
	s_waitcnt lgkmcnt(0)
	s_add_i32 s45, s41, 1
	s_cmp_lg_u32 s41, 2
	s_cselect_b32 s41, s45, 0
	s_add_i32 s44, s44, 1
	v_mfma_f32_16x16x32_bf16 v[44:47], v[178:181], v[194:197], v[44:47]
	v_mfma_f32_16x16x32_bf16 v[36:39], v[182:185], v[194:197], v[36:39]
	v_mfma_f32_16x16x32_bf16 v[28:31], v[186:189], v[194:197], v[28:31]
	v_mfma_f32_16x16x32_bf16 v[24:27], v[190:193], v[194:197], v[24:27]
	v_mfma_f32_16x16x32_bf16 v[20:23], v[178:181], v[198:201], v[20:23]
	v_mfma_f32_16x16x32_bf16 v[16:19], v[182:185], v[198:201], v[16:19]
	v_mfma_f32_16x16x32_bf16 v[12:15], v[186:189], v[198:201], v[12:15]
	v_mfma_f32_16x16x32_bf16 v[8:11], v[190:193], v[198:201], v[8:11]
	v_mfma_f32_16x16x32_bf16 v[4:7], v[178:181], v[202:205], v[4:7]
	v_mfma_f32_16x16x32_bf16 v[0:3], v[182:185], v[202:205], v[0:3]
	v_mfma_f32_16x16x32_bf16 v[32:35], v[186:189], v[202:205], v[32:35]
	v_mfma_f32_16x16x32_bf16 v[40:43], v[190:193], v[202:205], v[40:43]
	v_mfma_f32_16x16x32_bf16 v[48:51], v[178:181], v[206:209], v[48:51]
	v_mfma_f32_16x16x32_bf16 v[52:55], v[182:185], v[206:209], v[52:55]
	v_mfma_f32_16x16x32_bf16 v[56:59], v[186:189], v[206:209], v[56:59]
	v_mfma_f32_16x16x32_bf16 v[60:63], v[190:193], v[206:209], v[60:63]
	v_mfma_f32_16x16x32_bf16 v[44:47], v[210:213], v[226:229], v[44:47]
	v_mfma_f32_16x16x32_bf16 v[36:39], v[214:217], v[226:229], v[36:39]
	v_mfma_f32_16x16x32_bf16 v[28:31], v[218:221], v[226:229], v[28:31]
	v_mfma_f32_16x16x32_bf16 v[24:27], v[222:225], v[226:229], v[24:27]
	v_mfma_f32_16x16x32_bf16 v[20:23], v[210:213], v[230:233], v[20:23]
	v_mfma_f32_16x16x32_bf16 v[16:19], v[214:217], v[230:233], v[16:19]
	v_mfma_f32_16x16x32_bf16 v[12:15], v[218:221], v[230:233], v[12:15]
	v_mfma_f32_16x16x32_bf16 v[8:11], v[222:225], v[230:233], v[8:11]
	v_mfma_f32_16x16x32_bf16 v[4:7], v[210:213], v[234:237], v[4:7]
	v_mfma_f32_16x16x32_bf16 v[0:3], v[214:217], v[234:237], v[0:3]
	v_mfma_f32_16x16x32_bf16 v[32:35], v[218:221], v[234:237], v[32:35]
	v_mfma_f32_16x16x32_bf16 v[40:43], v[222:225], v[234:237], v[40:43]
	v_mfma_f32_16x16x32_bf16 v[48:51], v[210:213], v[238:241], v[48:51]
	v_mfma_f32_16x16x32_bf16 v[52:55], v[214:217], v[238:241], v[52:55]
	v_mfma_f32_16x16x32_bf16 v[56:59], v[218:221], v[238:241], v[56:59]
	v_mfma_f32_16x16x32_bf16 v[60:63], v[222:225], v[238:241], v[60:63]
	v_sub_co_u32_e64 v64, s[40:41], s33, 16
	s_nop 0
	v_readfirstlane_b32 s44, v64
	s_ashr_i32 s44, s44, 2
	s_add_i32 s44, s44, 1
	s_and_b64 s[40:41], s[40:41], exec
	v_readlane_b32 s40, v255, 6
	s_cselect_b32 s94, 0, s44
	s_mul_i32 s40, s40, 5
	s_add_i32 s40, s94, s40
	s_mulk_i32 s40, 0x6000
	s_ashr_i32 s41, s40, 31
	s_waitcnt vmcnt(6)
	s_add_u32 s40, s93, s40
	v_add_u32_e32 v84, 0, v81
	s_addc_u32 s41, s90, s41
	s_barrier
	v_add_u32_e32 v100, 0, v82
	v_add_u32_e32 v103, 0, v80
	ds_read_b128 v[64:67], v84 offset:0
	ds_read_b128 v[68:71], v84 offset:0x800
	ds_read_b128 v[72:75], v84 offset:0x1000
	ds_read_b128 v[84:87], v84 offset:0x1800
	ds_read_b128 v[88:91], v100 offset:0
	ds_read_b128 v[92:95], v100 offset:0x800
	ds_read_b128 v[96:99], v100 offset:0x1000
	ds_read_b128 v[104:107], v100 offset:0x1800
	v_add_u32_e32 v101, 0, v83
	ds_read_b128 v[108:111], v101 offset:0
	ds_read_b128 v[116:119], v101 offset:0x800
	ds_read_b128 v[120:123], v101 offset:0x1000
	ds_read_b128 v[124:127], v101 offset:0x1800
	ds_read_b128 v[128:131], v103 offset:0
	ds_read_b128 v[132:135], v103 offset:0x800
	ds_read_b128 v[136:139], v103 offset:0x1000
	s_waitcnt lgkmcnt(7)
	ds_read_b128 v[140:143], v103 offset:0x1800
	s_setprio 1
	v_mfma_f32_16x16x32_bf16 v[44:47], v[64:67], v[88:91], v[44:47]
	v_mfma_f32_16x16x32_bf16 v[36:39], v[68:71], v[88:91], v[36:39]
	v_mfma_f32_16x16x32_bf16 v[28:31], v[72:75], v[88:91], v[28:31]
	v_mfma_f32_16x16x32_bf16 v[24:27], v[84:87], v[88:91], v[24:27]
	v_mfma_f32_16x16x32_bf16 v[20:23], v[64:67], v[92:95], v[20:23]
	v_mfma_f32_16x16x32_bf16 v[16:19], v[68:71], v[92:95], v[16:19]
	v_mfma_f32_16x16x32_bf16 v[12:15], v[72:75], v[92:95], v[12:15]
	v_mfma_f32_16x16x32_bf16 v[8:11], v[84:87], v[92:95], v[8:11]
	v_mfma_f32_16x16x32_bf16 v[4:7], v[64:67], v[96:99], v[4:7]
	v_mfma_f32_16x16x32_bf16 v[0:3], v[68:71], v[96:99], v[0:3]
	v_mfma_f32_16x16x32_bf16 v[32:35], v[72:75], v[96:99], v[32:35]
	v_mfma_f32_16x16x32_bf16 v[40:43], v[84:87], v[96:99], v[40:43]
	v_mfma_f32_16x16x32_bf16 v[48:51], v[64:67], v[104:107], v[48:51]
	v_mfma_f32_16x16x32_bf16 v[52:55], v[68:71], v[104:107], v[52:55]
	v_mfma_f32_16x16x32_bf16 v[56:59], v[72:75], v[104:107], v[56:59]
	v_mfma_f32_16x16x32_bf16 v[60:63], v[84:87], v[104:107], v[60:63]
	s_setprio 0
	s_waitcnt lgkmcnt(0)
	s_setprio 1
	v_mfma_f32_16x16x32_bf16 v[44:47], v[108:111], v[128:131], v[44:47]
	v_mfma_f32_16x16x32_bf16 v[36:39], v[116:119], v[128:131], v[36:39]
	v_mfma_f32_16x16x32_bf16 v[28:31], v[120:123], v[128:131], v[28:31]
	v_mfma_f32_16x16x32_bf16 v[24:27], v[124:127], v[128:131], v[24:27]
	v_mfma_f32_16x16x32_bf16 v[20:23], v[108:111], v[132:135], v[20:23]
	v_mfma_f32_16x16x32_bf16 v[16:19], v[116:119], v[132:135], v[16:19]
	v_mfma_f32_16x16x32_bf16 v[12:15], v[120:123], v[132:135], v[12:15]
	v_mfma_f32_16x16x32_bf16 v[8:11], v[124:127], v[132:135], v[8:11]
	v_mfma_f32_16x16x32_bf16 v[4:7], v[108:111], v[136:139], v[4:7]
	v_mfma_f32_16x16x32_bf16 v[0:3], v[116:119], v[136:139], v[0:3]
	v_mfma_f32_16x16x32_bf16 v[32:35], v[120:123], v[136:139], v[32:35]
	v_mfma_f32_16x16x32_bf16 v[40:43], v[124:127], v[136:139], v[40:43]
	v_mfma_f32_16x16x32_bf16 v[48:51], v[108:111], v[140:143], v[48:51]
	v_mfma_f32_16x16x32_bf16 v[52:55], v[116:119], v[140:143], v[52:55]
	v_mfma_f32_16x16x32_bf16 v[56:59], v[120:123], v[140:143], v[56:59]
	v_mfma_f32_16x16x32_bf16 v[60:63], v[124:127], v[140:143], v[60:63]
	s_setprio 0
	s_waitcnt vmcnt(0)
	s_add_i32 s44, 0, 0xc000
	v_add_u32_e32 v81, s44, v81
	v_add_u32_e32 v96, s44, v82
	s_barrier
	v_add_u32_e32 v100, s44, v83
	v_add_u32_e32 v101, s44, v80
	ds_read_b128 v[64:67], v81 offset:0
	ds_read_b128 v[68:71], v81 offset:0x800
	ds_read_b128 v[72:75], v81 offset:0x1000
	ds_read_b128 v[80:83], v81 offset:0x1800
	ds_read_b128 v[84:87], v96 offset:0
	ds_read_b128 v[88:91], v96 offset:0x800
	ds_read_b128 v[92:95], v96 offset:0x1000
	ds_read_b128 v[96:99], v96 offset:0x1800
	ds_read_b128 v[104:107], v100 offset:0
	ds_read_b128 v[108:111], v100 offset:0x800
	ds_read_b128 v[116:119], v100 offset:0x1000
	ds_read_b128 v[120:123], v100 offset:0x1800
	ds_read_b128 v[124:127], v101 offset:0
	ds_read_b128 v[128:131], v101 offset:0x800
	ds_read_b128 v[132:135], v101 offset:0x1000
	s_nop 0
	s_waitcnt lgkmcnt(7)
	ds_read_b128 v[136:139], v101 offset:0x1800
	s_setprio 1
	v_mfma_f32_16x16x32_bf16 v[44:47], v[64:67], v[84:87], v[44:47]
	v_mfma_f32_16x16x32_bf16 v[36:39], v[68:71], v[84:87], v[36:39]
	v_mfma_f32_16x16x32_bf16 v[28:31], v[72:75], v[84:87], v[28:31]
	v_mfma_f32_16x16x32_bf16 v[24:27], v[80:83], v[84:87], v[24:27]
	v_mfma_f32_16x16x32_bf16 v[20:23], v[64:67], v[88:91], v[20:23]
	v_mfma_f32_16x16x32_bf16 v[16:19], v[68:71], v[88:91], v[16:19]
	v_mfma_f32_16x16x32_bf16 v[12:15], v[72:75], v[88:91], v[12:15]
	v_mfma_f32_16x16x32_bf16 v[8:11], v[80:83], v[88:91], v[8:11]
	v_mfma_f32_16x16x32_bf16 v[4:7], v[64:67], v[92:95], v[4:7]
	v_mfma_f32_16x16x32_bf16 v[0:3], v[68:71], v[92:95], v[0:3]
	v_mfma_f32_16x16x32_bf16 v[32:35], v[72:75], v[92:95], v[32:35]
	v_mfma_f32_16x16x32_bf16 v[84:87], v[80:83], v[92:95], v[40:43]
	v_mfma_f32_16x16x32_bf16 v[72:75], v[72:75], v[96:99], v[56:59]
	v_mfma_f32_16x16x32_bf16 v[80:83], v[80:83], v[96:99], v[60:63]
	v_mfma_f32_16x16x32_bf16 v[88:91], v[64:67], v[96:99], v[48:51]
	v_mfma_f32_16x16x32_bf16 v[92:95], v[68:71], v[96:99], v[52:55]
	s_setprio 0
	s_waitcnt lgkmcnt(0)
	s_setprio 1
	v_mfma_f32_16x16x32_bf16 v[96:99], v[104:107], v[124:127], v[44:47]
	v_mfma_f32_16x16x32_bf16 v[140:143], v[108:111], v[124:127], v[36:39]
	v_mfma_f32_16x16x32_bf16 v[68:71], v[116:119], v[124:127], v[28:31]
	v_mfma_f32_16x16x32_bf16 v[64:67], v[120:123], v[124:127], v[24:27]
	v_mfma_f32_16x16x32_bf16 v[60:63], v[104:107], v[128:131], v[20:23]
	v_mfma_f32_16x16x32_bf16 v[56:59], v[108:111], v[128:131], v[16:19]
	v_mfma_f32_16x16x32_bf16 v[52:55], v[116:119], v[128:131], v[12:15]
	v_mfma_f32_16x16x32_bf16 v[48:51], v[120:123], v[128:131], v[8:11]
	v_mfma_f32_16x16x32_bf16 v[44:47], v[104:107], v[132:135], v[4:7]
	v_mfma_f32_16x16x32_bf16 v[40:43], v[108:111], v[132:135], v[0:3]
	v_mfma_f32_16x16x32_bf16 v[36:39], v[116:119], v[132:135], v[32:35]
	v_mfma_f32_16x16x32_bf16 v[32:35], v[120:123], v[132:135], v[84:87]
	v_mfma_f32_16x16x32_bf16 v[20:23], v[104:107], v[136:139], v[88:91]
	v_mfma_f32_16x16x32_bf16 v[16:19], v[108:111], v[136:139], v[92:95]
	v_mfma_f32_16x16x32_bf16 v[8:11], v[116:119], v[136:139], v[72:75]
	v_mfma_f32_16x16x32_bf16 v[0:3], v[120:123], v[136:139], v[80:83]
	s_setprio 0
	s_lshl_b32 s44, s46, 7
	v_lshlrev_b32_e32 v103, 6, v77
	v_lshlrev_b32_e32 v4, 3, v79
	v_or3_b32 v72, v4, s44, v103
	v_ashrrev_i32_e32 v73, 31, v72
	v_lshl_add_u64 v[4:5], v[72:73], 2, s[40:41]
	s_mov_b64 s[40:41], 0x5000
	v_lshl_add_u64 v[12:13], v[4:5], 0, s[40:41]
	s_movk_i32 s40, 0x5000
	v_add_co_u32_e32 v4, vcc, s40, v4
	v_lshlrev_b32_e32 v115, 6, v78
	s_nop 0
	v_addc_co_u32_e32 v5, vcc, 0, v5, vcc
	v_cmp_lt_i32_e32 vcc, v163, v164
	s_lshl_b32 s63, s33, 8
	global_load_dwordx4 v[28:31], v[4:5], off
	global_load_dwordx4 v[24:27], v[12:13], off offset:16
	s_nop 0
	global_load_dwordx4 v[4:7], v[12:13], off offset:144
	s_nop 0
	global_load_dwordx4 v[12:15], v[12:13], off offset:128
	v_cndmask_b32_e32 v74, v162, v163, vcc
	v_cmp_lt_i32_e32 vcc, v165, v164
	v_lshlrev_b32_e32 v105, 2, v74
	s_nop 0
	v_cndmask_b32_e32 v74, v162, v165, vcc
	v_lshlrev_b32_e32 v104, 2, v74
	v_lshl_add_u32 v74, v77, 8, v115
	v_or_b32_e32 v106, v74, v114
	v_add_u32_e32 v74, s63, v115
	v_or_b32_e32 v82, v74, v114
	v_cmp_gt_i32_e64 s[40:41], s64, v82
	v_ashrrev_i32_e32 v74, 31, v82
	v_cmp_gt_u32_e32 vcc, 16, v76
	v_cndmask_b32_e64 v83, 0, v74, s[40:41]
	v_lshlrev_b64 v[74:75], 11, v[82:83]
	v_lshl_add_u64 v[74:75], s[30:31], 0, v[74:75]
	v_lshl_add_u64 v[100:101], v[72:73], 1, v[74:75]
	global_load_dwordx4 v[74:77], v[100:101], off
	global_load_dwordx4 v[108:111], v[100:101], off offset:64
	v_lshl_add_u32 v106, v106, 3, 0
	s_waitcnt vmcnt(0)
	v_lshlrev_b32_e32 v78, 16, v74
	v_and_b32_e32 v79, 0xffff0000, v74
	v_lshlrev_b32_e32 v74, 16, v75
	v_and_b32_e32 v75, 0xffff0000, v75
	v_pk_mul_f32 v[74:75], v[74:75], s[96:97] op_sel_hi:[1,0]
	v_pk_mul_f32 v[78:79], v[78:79], s[96:97] op_sel_hi:[1,0]
	v_pk_fma_f32 v[80:81], v[98:99], v[30:31], v[74:75]
	v_lshlrev_b32_e32 v74, 16, v76
	v_and_b32_e32 v75, 0xffff0000, v76
	v_lshlrev_b32_e32 v76, 16, v77
	v_and_b32_e32 v77, 0xffff0000, v77
	v_pk_mul_f32 v[76:77], v[76:77], s[96:97] op_sel_hi:[1,0]
	v_pk_mul_f32 v[74:75], v[74:75], s[96:97] op_sel_hi:[1,0]
	v_pk_fma_f32 v[76:77], v[142:143], v[26:27], v[76:77]
	v_pk_fma_f32 v[78:79], v[96:97], v[28:29], v[78:79]
	v_mul_f32_e32 v89, v80, v80
	v_pk_fma_f32 v[74:75], v[140:141], v[24:25], v[74:75]
	v_mul_f32_e32 v88, v76, v76
	v_lshlrev_b32_e32 v98, 16, v108
	v_and_b32_e32 v99, 0xffff0000, v108
	v_lshlrev_b32_e32 v100, 16, v109
	v_and_b32_e32 v101, 0xffff0000, v109
	v_add_f32_e32 v84, v78, v79
	v_add_f32_e32 v86, v80, v81
	v_mul_f32_e32 v93, v78, v78
	v_mul_f32_e32 v95, v79, v79
	v_mul_f32_e32 v91, v81, v81
	v_mul_f32_e32 v85, v74, v74
	v_mul_f32_e32 v87, v75, v75
	v_pk_fma_f32 v[96:97], v[76:77], v[76:77], v[88:89] op_sel_hi:[1,1,0]
	v_pk_mul_f32 v[98:99], v[98:99], s[96:97] op_sel_hi:[1,0]
	v_pk_mul_f32 v[100:101], v[100:101], s[96:97] op_sel_hi:[1,0]
	v_mov_b32_e32 v92, v74
	v_mov_b32_e32 v94, v75
	v_mov_b32_e32 v88, v76
	v_mov_b32_e32 v90, v77
	v_pk_fma_f32 v[70:71], v[70:71], v[14:15], v[100:101]
	v_pk_fma_f32 v[68:69], v[68:69], v[12:13], v[98:99]
	v_lshlrev_b32_e32 v116, 16, v110
	v_and_b32_e32 v117, 0xffff0000, v110
	v_lshlrev_b32_e32 v110, 16, v111
	v_and_b32_e32 v111, 0xffff0000, v111
	v_pk_add_f32 v[92:93], v[92:93], v[94:95]
	v_pk_add_f32 v[88:89], v[88:89], v[90:91]
	v_pk_add_f32 v[84:85], v[84:85], v[86:87]
	v_mov_b32_e32 v96, v145
	v_mul_f32_e32 v109, v68, v68
	v_mul_f32_e32 v113, v69, v69
	v_mul_f32_e32 v99, v70, v70
	v_mul_f32_e32 v101, v71, v71
	v_pk_mul_f32 v[116:117], v[116:117], s[96:97] op_sel_hi:[1,0]
	v_pk_mul_f32 v[110:111], v[110:111], s[96:97] op_sel_hi:[1,0]
	v_pk_add_f32 v[88:89], v[92:93], v[88:89]
	v_pk_add_f32 v[84:85], v[84:85], v[96:97]
	v_mov_b32_e32 v108, v68
	v_mov_b32_e32 v112, v69
	v_mov_b32_e32 v98, v70
	v_mov_b32_e32 v100, v71
	v_pk_fma_f32 v[66:67], v[66:67], v[6:7], v[110:111]
	v_pk_fma_f32 v[64:65], v[64:65], v[4:5], v[116:117]
	v_pk_add_f32 v[84:85], v[88:89], v[84:85]
	v_pk_add_f32 v[86:87], v[108:109], v[112:113]
	v_pk_add_f32 v[88:89], v[98:99], v[100:101]
	v_mul_f32_e32 v111, v64, v64
	v_mul_f32_e32 v117, v65, v65
	v_mul_f32_e32 v119, v66, v66
	v_mul_f32_e32 v121, v67, v67
	v_pk_add_f32 v[86:87], v[86:87], v[88:89]
	v_mov_b32_e32 v110, v64
	v_mov_b32_e32 v116, v65
	v_mov_b32_e32 v118, v66
	v_mov_b32_e32 v120, v67
	v_pk_add_f32 v[84:85], v[84:85], v[86:87]
	v_pk_add_f32 v[86:87], v[110:111], v[116:117]
	v_pk_add_f32 v[88:89], v[118:119], v[120:121]
	s_nop 0
	v_pk_add_f32 v[86:87], v[86:87], v[88:89]
	s_nop 0
	v_pk_add_f32 v[84:85], v[84:85], v[86:87]
	ds_bpermute_b32 v86, v105, v84
	ds_bpermute_b32 v87, v105, v85
	s_waitcnt lgkmcnt(0)
	v_pk_add_f32 v[84:85], v[84:85], v[86:87]
	ds_bpermute_b32 v86, v104, v84
	ds_bpermute_b32 v87, v104, v85
	s_and_saveexec_b64 s[40:41], vcc
	s_cbranch_execz .LBB0_720
	v_add_u32_e32 v83, 0x24000, v106
	s_waitcnt lgkmcnt(0)
	v_pk_add_f32 v[84:85], v[84:85], v[86:87]
	ds_write_b64 v83, v[84:85]
